# LayerNorm phases: the two per-row wave reductions use DPP / permlane-swap steps (same lane pairs, same adds) instead of 6 ds_bpermute round trips each
# speedup vs baseline: 1.0008x; 1.0008x over previous
; template <int MODE>
; __device__ __forceinline__ void lnmod_phase(const float* src, float* dst, float* stats, bf16* H, const bf16* zb, const float* lng, const float* lnb, const float* ada_mod  , int lane, int wave, int G) {
;     ...
;         for (int i = 0; i < 32; ++i) {
;             const int r = chunk * 32 + i;
; #pragma unroll
;             for (int j = 0; j < 4; ++j) v[j] = nx[j];
;             if (i + 1 < 32) {
; #pragma unroll
;                 for (int j = 0; j < 4; ++j) { if (MODE != 0) { const v2u w = gld<v2u>(zb + ((size_t)chunk * 32 + i + 1) * D + 4 * lane + 256 * j); nx[j] = (f32x4){__builtin_bit_cast(float, w.x << 16), __builtin_bit_cast(float, w.x & 0xffff0000u), __builtin_bit_cast(float, w.y << 16), __builtin_bit_cast(float, w.y & 0xffff0000u)}; } else nx[j] = gld<f32x4>(rp + (size_t)(i + 1) * D + 256 * j); }
;             }
;             if (MODE != 0) {
;                 float s = 0.f;
; #pragma unroll
;                 for (int j = 0; j < 4; ++j) s += (v[j].x + v[j].y) + (v[j].z + v[j].w);
;                 const float mean = wave_sum(s) * (1.f / D); float s2 = 0.f;
; #pragma unroll
;                 for (int j = 0; j < 4; ++j) { v[j] = v[j] - mean; s2 += (v[j].x * v[j].x + v[j].y * v[j].y) + (v[j].z * v[j].z + v[j].w * v[j].w); }
;                 const float rstd = 1.f / sqrtf(wave_sum(s2) * (1.f / D) + LN_EPS);
;                 if (MODE == 1 && lane == 0) gst<f32x2v>(stats + 2 * (size_t)r, (f32x2v){mean, rstd});
; #pragma unroll
;                 for (int j = 0; j < 4; ++j) v[j] = v[j] * rstd * g[j] + bb[j];
.LBB0_1267:
	v_mov_b32_e32 v92, v78
	v_mov_b32_e32 v77, v79
	v_pk_add_f32 v[100:101], v[92:93], v[76:77]
	v_mov_b32_e32 v90, v82
	v_mov_b32_e32 v81, v83
	v_add_f32_e32 v77, v100, v101
	v_pk_add_f32 v[100:101], v[90:91], v[80:81]
	v_add_f32_e32 v99, 0, v77
	v_pk_add_f32 v[100:101], v[100:101], v[100:101] op_sel_hi:[0,1]
	v_add_f32_e32 v87, v84, v85
	v_add_f32_e32 v89, v94, v95
	v_mov_b32_e32 v97, v101
	v_pk_add_f32 v[102:103], v[86:87], v[88:89]
	v_pk_add_f32 v[100:101], v[96:97], v[98:99]
	v_mov_b32_e32 v105, v83
	v_pk_add_f32 v[100:101], v[102:103], v[100:101]
	v_lshl_add_u64 v[102:103], v[58:59], 0, s[16:17]
	v_add_f32_e32 v77, v100, v101
	v_mov_b32_e32 v101, v79
	v_add_co_u32_e32 v92, vcc, s76, v102
	v_mov_b32_e32 v100, v93
	s_nop 1
	v_add_f32_dpp v77, v77, v77 quad_perm:[1,0,3,2] row_mask:0xf bank_mask:0xf
	v_addc_co_u32_e32 v93, vcc, 0, v103, vcc
	global_load_dwordx2 v[112:113], v[92:93], off offset:2048
	global_load_dwordx2 v[108:109], v[92:93], off offset:2560
	global_load_dwordx2 v[106:107], v[92:93], off offset:3072
	global_load_dwordx2 v[102:103], v[92:93], off offset:3584
	v_mov_b32_e32 v104, v91
	s_nop 1
	v_add_f32_dpp v77, v77, v77 quad_perm:[2,3,0,1] row_mask:0xf bank_mask:0xf
	v_mov_b32_e32 v111, v95
	v_mov_b32_e32 v110, v94
	v_mov_b32_e32 v115, v98
	v_mov_b32_e32 v114, v96
	s_nop 1
	v_mov_b32_dpp v81, v77 row_half_mirror row_mask:0xf bank_mask:0xf
	s_nop 1
	v_add_f32_dpp v77, v81, v77 quad_perm:[3,2,1,0] row_mask:0xf bank_mask:0xf
	s_ashr_i32 s19, s18, 31
	s_nop 1
	v_mov_b32_dpp v81, v77 row_mirror row_mask:0xf bank_mask:0xf
	s_nop 1
	v_add_f32_dpp v77, v81, v77 row_half_mirror row_mask:0xf bank_mask:0xf
	v_mov_b32_e32 v79, v77
	s_nop 1
	v_permlane16_swap_b32_e32 v79, v77
	v_add_f32_e32 v77, v79, v77
	v_mov_b32_e32 v79, v77
	s_nop 1
	v_permlane32_swap_b32_e32 v79, v77
	v_add_f32_e32 v77, v79, v77
	v_fmac_f32_e32 v101, 0xba800000, v77
	v_fmac_f32_e32 v78, 0xba800000, v77
	v_fmac_f32_e32 v100, 0xba800000, v77
	v_fmac_f32_e32 v76, 0xba800000, v77
	v_mul_f32_e32 v79, v78, v78
	v_mul_f32_e32 v81, v101, v101
	v_fmac_f32_e32 v79, v76, v76
	v_fmac_f32_e32 v81, v100, v100
	v_fmac_f32_e32 v105, 0xba800000, v77
	v_fmac_f32_e32 v82, 0xba800000, v77
	v_add_f32_e32 v79, v79, v81
	v_fmac_f32_e32 v104, 0xba800000, v77
	v_fmac_f32_e32 v80, 0xba800000, v77
	v_mul_f32_e32 v81, v82, v82
	v_mul_f32_e32 v83, v105, v105
	v_fmac_f32_e32 v81, v80, v80
	v_fmac_f32_e32 v83, v104, v104
	v_add_f32_e32 v81, v81, v83
	v_fmac_f32_e32 v111, 0xba800000, v77
	v_fmac_f32_e32 v85, 0xba800000, v77
	v_add_f32_e32 v79, v79, v81
	v_fmac_f32_e32 v110, 0xba800000, v77
	v_fmac_f32_e32 v84, 0xba800000, v77
	v_mul_f32_e32 v81, v85, v85
	v_mul_f32_e32 v83, v111, v111
	v_fmac_f32_e32 v81, v84, v84
	v_fmac_f32_e32 v83, v110, v110
	v_add_f32_e32 v81, v81, v83
	v_fmac_f32_e32 v115, 0xba800000, v77
	v_fmac_f32_e32 v88, 0xba800000, v77
	v_add_f32_e32 v79, v81, v79
	v_fmac_f32_e32 v114, 0xba800000, v77
	v_fmac_f32_e32 v86, 0xba800000, v77
	v_mul_f32_e32 v81, v88, v88
	v_mul_f32_e32 v83, v115, v115
	v_fmac_f32_e32 v81, v86, v86
	v_fmac_f32_e32 v83, v114, v114
	v_add_f32_e32 v81, v81, v83
	v_add_f32_e32 v79, v81, v79
	s_nop 1
	v_add_f32_dpp v79, v79, v79 quad_perm:[1,0,3,2] row_mask:0xf bank_mask:0xf
	s_nop 1
	v_add_f32_dpp v79, v79, v79 quad_perm:[2,3,0,1] row_mask:0xf bank_mask:0xf
	s_nop 1
	v_mov_b32_dpp v81, v79 row_half_mirror row_mask:0xf bank_mask:0xf
	s_nop 1
	v_add_f32_dpp v79, v81, v79 quad_perm:[3,2,1,0] row_mask:0xf bank_mask:0xf
	s_nop 1
	v_mov_b32_dpp v81, v79 row_mirror row_mask:0xf bank_mask:0xf
	s_nop 1
	v_add_f32_dpp v79, v81, v79 row_half_mirror row_mask:0xf bank_mask:0xf
	v_mov_b32_e32 v81, v79
	s_nop 1
	v_permlane16_swap_b32_e32 v81, v79
	v_add_f32_e32 v79, v81, v79
	v_mov_b32_e32 v81, v79
	s_nop 1
	v_permlane32_swap_b32_e32 v81, v79
	v_add_f32_e32 v79, v81, v79
	v_fmamk_f32 v79, v79, 0x3a800000, v205
	v_mul_f32_e32 v81, 0x4f800000, v79
	v_cmp_gt_f32_e32 vcc, s34, v79
	s_nop 1
	v_cndmask_b32_e32 v79, v79, v81, vcc
	v_sqrt_f32_e32 v81, v79
	s_nop 0
	v_add_u32_e32 v83, -1, v81
	v_fma_f32 v87, -v83, v81, v79
	v_cmp_ge_f32_e64 s[0:1], 0, v87
	v_add_u32_e32 v87, 1, v81
	s_nop 0
	v_cndmask_b32_e64 v83, v81, v83, s[0:1]
	v_fma_f32 v81, -v87, v81, v79
	v_cmp_lt_f32_e64 s[0:1], 0, v81
	s_nop 1
	v_cndmask_b32_e64 v81, v83, v87, s[0:1]
	v_mul_f32_e32 v83, 0x37800000, v81
	v_cndmask_b32_e32 v81, v81, v83, vcc
	v_cmp_class_f32_e32 vcc, v79, v204
	s_nop 1
	v_cndmask_b32_e32 v79, v81, v79, vcc
	v_div_scale_f32 v81, s[0:1], v79, v79, 1.0
	v_rcp_f32_e32 v83, v81
	s_nop 0
	v_fma_f32 v87, -v81, v83, 1.0
	v_fmac_f32_e32 v83, v87, v83
	v_div_scale_f32 v87, vcc, 1.0, v79, 1.0
	v_mul_f32_e32 v89, v87, v83
	v_fma_f32 v90, -v81, v89, v87
	v_fmac_f32_e32 v89, v90, v83
	v_fma_f32 v81, -v81, v89, v87
	v_div_fmas_f32 v81, v81, v83, v89
	v_div_fixup_f32 v90, v81, v79, 1.0
	s_and_saveexec_b64 s[0:1], s[4:5]
	s_cbranch_execz .LBB0_1266
	s_lshl_b64 s[42:43], s[18:19], 3
	s_add_u32 s42, s74, s42
	v_mul_f32_e32 v92, 0x3a800000, v77
	s_addc_u32 s43, s75, s43
	v_mov_b32_e32 v93, v90
	global_store_dwordx2 v165, v[92:93], s[42:43]
	s_branch .LBB0_1266
; template <int MODE>
; __device__ __forceinline__ void lnmod_phase(const float* src, float* dst, float* stats, bf16* H, const bf16* zb, const float* lng, const float* lnb, const float* ada_mod  , int lane, int wave, int G) {
;     ...
;             if (MODE != 0) {
;                 float s = 0.f;
; #pragma unroll
;                 for (int j = 0; j < 4; ++j) s += (v[j].x + v[j].y) + (v[j].z + v[j].w);
;                 const float mean = wave_sum(s) * (1.f / D); float s2 = 0.f;
; #pragma unroll
;                 for (int j = 0; j < 4; ++j) { v[j] = v[j] - mean; s2 += (v[j].x * v[j].x + v[j].y * v[j].y) + (v[j].z * v[j].z + v[j].w * v[j].w); }
;                 const float rstd = 1.f / sqrtf(wave_sum(s2) * (1.f / D) + LN_EPS);
;                 if (MODE == 1 && lane == 0) gst<f32x2v>(stats + 2 * (size_t)r, (f32x2v){mean, rstd});
; #pragma unroll
;                 for (int j = 0; j < 4; ++j) v[j] = v[j] * rstd * g[j] + bb[j];
.LBB0_1269:
	v_mov_b32_e32 v77, v93
	v_mov_b32_e32 v81, v91
	v_pk_add_f32 v[100:101], v[76:77], v[78:79]
	v_pk_add_f32 v[102:103], v[80:81], v[82:83]
	v_add_f32_e32 v77, v100, v101
	v_pk_add_f32 v[102:103], v[102:103], v[102:103] op_sel:[0,1] op_sel_hi:[1,0]
	v_add_f32_e32 v100, 0, v77
	v_add_f32_e32 v104, v84, v85
	v_add_f32_e32 v106, v94, v95
	v_mov_b32_e32 v101, v86
	v_mov_b32_e32 v103, v88
	v_mov_b32_e32 v105, v96
	v_mov_b32_e32 v107, v98
	v_pk_add_f32 v[100:101], v[100:101], v[102:103]
	v_pk_add_f32 v[102:103], v[104:105], v[106:107]
	s_lshl_b32 s15, s14, 5
	v_pk_add_f32 v[100:101], v[100:101], v[102:103]
	s_nop 0
	v_add_f32_e32 v77, v100, v101
	s_nop 1
	v_add_f32_dpp v77, v77, v77 quad_perm:[1,0,3,2] row_mask:0xf bank_mask:0xf
	s_nop 1
	v_add_f32_dpp v77, v77, v77 quad_perm:[2,3,0,1] row_mask:0xf bank_mask:0xf
	s_nop 1
	v_mov_b32_dpp v81, v77 row_half_mirror row_mask:0xf bank_mask:0xf
	s_nop 1
	v_add_f32_dpp v77, v81, v77 quad_perm:[3,2,1,0] row_mask:0xf bank_mask:0xf
	s_nop 1
	v_mov_b32_dpp v81, v77 row_mirror row_mask:0xf bank_mask:0xf
	s_nop 1
	v_add_f32_dpp v77, v81, v77 row_half_mirror row_mask:0xf bank_mask:0xf
	v_mov_b32_e32 v81, v77
	s_nop 1
	v_permlane16_swap_b32_e32 v81, v77
	v_add_f32_e32 v77, v81, v77
	v_mov_b32_e32 v81, v77
	s_nop 1
	v_permlane32_swap_b32_e32 v81, v77
	v_add_f32_e32 v77, v81, v77
	v_fmac_f32_e32 v79, 0xba800000, v77
	v_fmac_f32_e32 v78, 0xba800000, v77
	v_fmac_f32_e32 v83, 0xba800000, v77
	v_fmac_f32_e32 v82, 0xba800000, v77
	v_fmac_f32_e32 v93, 0xba800000, v77
	v_fmac_f32_e32 v76, 0xba800000, v77
	v_fmac_f32_e32 v91, 0xba800000, v77
	v_fmac_f32_e32 v80, 0xba800000, v77
	v_mul_f32_e32 v81, v78, v78
	v_mul_f32_e32 v87, v79, v79
	v_mul_f32_e32 v89, v82, v82
	v_mul_f32_e32 v90, v83, v83
	v_fmac_f32_e32 v81, v76, v76
	v_fmac_f32_e32 v87, v93, v93
	v_fmac_f32_e32 v89, v80, v80
	v_fmac_f32_e32 v90, v91, v91
	v_add_f32_e32 v81, v81, v87
	v_add_f32_e32 v87, v89, v90
	v_fmac_f32_e32 v95, 0xba800000, v77
	v_fmac_f32_e32 v85, 0xba800000, v77
	v_add_f32_e32 v81, v81, v87
	v_fmac_f32_e32 v94, 0xba800000, v77
	v_fmac_f32_e32 v84, 0xba800000, v77
	v_mul_f32_e32 v87, v85, v85
	v_mul_f32_e32 v89, v95, v95
	v_fmac_f32_e32 v87, v84, v84
	v_fmac_f32_e32 v89, v94, v94
	v_add_f32_e32 v87, v87, v89
	v_fmac_f32_e32 v98, 0xba800000, v77
	v_fmac_f32_e32 v88, 0xba800000, v77
	v_add_f32_e32 v81, v87, v81
	v_fmac_f32_e32 v96, 0xba800000, v77
	v_fmac_f32_e32 v86, 0xba800000, v77
	v_mul_f32_e32 v87, v88, v88
	v_mul_f32_e32 v89, v98, v98
	v_fmac_f32_e32 v87, v86, v86
	v_fmac_f32_e32 v89, v96, v96
	v_add_f32_e32 v87, v87, v89
	v_add_f32_e32 v81, v87, v81
	s_nop 1
	v_add_f32_dpp v81, v81, v81 quad_perm:[1,0,3,2] row_mask:0xf bank_mask:0xf
	s_nop 1
	v_add_f32_dpp v81, v81, v81 quad_perm:[2,3,0,1] row_mask:0xf bank_mask:0xf
	s_nop 1
	v_mov_b32_dpp v87, v81 row_half_mirror row_mask:0xf bank_mask:0xf
	s_nop 1
	v_add_f32_dpp v81, v87, v81 quad_perm:[3,2,1,0] row_mask:0xf bank_mask:0xf
	s_nop 1
	v_mov_b32_dpp v87, v81 row_mirror row_mask:0xf bank_mask:0xf
	s_nop 1
	v_add_f32_dpp v81, v87, v81 row_half_mirror row_mask:0xf bank_mask:0xf
	v_mov_b32_e32 v87, v81
	s_nop 1
	v_permlane16_swap_b32_e32 v87, v81
	v_add_f32_e32 v81, v87, v81
	v_mov_b32_e32 v87, v81
	s_nop 1
	v_permlane32_swap_b32_e32 v87, v81
	v_add_f32_e32 v81, v87, v81
	v_fmamk_f32 v81, v81, 0x3a800000, v205
	v_mul_f32_e32 v87, 0x4f800000, v81
	v_cmp_gt_f32_e32 vcc, s34, v81
	s_nop 1
	v_cndmask_b32_e32 v81, v81, v87, vcc
	v_sqrt_f32_e32 v87, v81
	s_nop 0
	v_add_u32_e32 v89, -1, v87
	v_add_u32_e32 v90, 1, v87
	v_fma_f32 v92, -v89, v87, v81
	v_fma_f32 v97, -v90, v87, v81
	v_cmp_ge_f32_e64 s[0:1], 0, v92
	s_nop 1
	v_cndmask_b32_e64 v87, v87, v89, s[0:1]
	v_cmp_lt_f32_e64 s[0:1], 0, v97
	s_nop 1
	v_cndmask_b32_e64 v87, v87, v90, s[0:1]
	v_mul_f32_e32 v89, 0x37800000, v87
	v_cndmask_b32_e32 v87, v87, v89, vcc
	v_cmp_class_f32_e32 vcc, v81, v204
	s_nop 1
	v_cndmask_b32_e32 v81, v87, v81, vcc
	v_div_scale_f32 v87, s[0:1], v81, v81, 1.0
	v_rcp_f32_e32 v89, v87
	v_div_scale_f32 v90, vcc, 1.0, v81, 1.0
	s_or_b32 s0, s15, 31
	v_fma_f32 v92, -v87, v89, 1.0
	v_fmac_f32_e32 v89, v92, v89
	v_mul_f32_e32 v92, v90, v89
	v_fma_f32 v97, -v87, v92, v90
	v_fmac_f32_e32 v92, v97, v89
	v_fma_f32 v87, -v87, v92, v90
	v_div_fmas_f32 v87, v87, v89, v92
	v_div_fixup_f32 v90, v87, v81, 1.0
	s_ashr_i32 s1, s0, 31
	s_and_saveexec_b64 s[16:17], s[4:5]
	s_cbranch_execz .LBB0_1264
	s_lshl_b64 s[18:19], s[0:1], 3
	s_add_u32 s18, s74, s18
	v_mul_f32_e32 v100, 0x3a800000, v77
	s_addc_u32 s19, s75, s19
	v_mov_b32_e32 v101, v90
	global_store_dwordx2 v165, v[100:101], s[18:19]
	s_branch .LBB0_1264

; template <int MODE>
; __device__ __forceinline__ void lnmod_phase(const float* src, float* dst, float* stats, bf16* H, const bf16* zb, const float* lng, const float* lnb, const float* ada_mod  , int lane, int wave, int G) {
;     ...
;         for (int i = 0; i < 32; ++i) {
;             const int r = chunk * 32 + i;
; #pragma unroll
;             for (int j = 0; j < 4; ++j) v[j] = nx[j];
;             if (i + 1 < 32) {
; #pragma unroll
;                 for (int j = 0; j < 4; ++j) { if (MODE != 0) { const v2u w = gld<v2u>(zb + ((size_t)chunk * 32 + i + 1) * D + 4 * lane + 256 * j); nx[j] = (f32x4){__builtin_bit_cast(float, w.x << 16), __builtin_bit_cast(float, w.x & 0xffff0000u), __builtin_bit_cast(float, w.y << 16), __builtin_bit_cast(float, w.y & 0xffff0000u)}; } else nx[j] = gld<f32x4>(rp + (size_t)(i + 1) * D + 256 * j); }
;             }
;             if (MODE != 0) {
;                 float s = 0.f;
; #pragma unroll
;                 for (int j = 0; j < 4; ++j) s += (v[j].x + v[j].y) + (v[j].z + v[j].w);
;                 const float mean = wave_sum(s) * (1.f / D); float s2 = 0.f;
; #pragma unroll
;                 for (int j = 0; j < 4; ++j) { v[j] = v[j] - mean; s2 += (v[j].x * v[j].x + v[j].y * v[j].y) + (v[j].z * v[j].z + v[j].w * v[j].w); }
;                 const float rstd = 1.f / sqrtf(wave_sum(s2) * (1.f / D) + LN_EPS);
;                 if (MODE == 1 && lane == 0) gst<f32x2v>(stats + 2 * (size_t)r, (f32x2v){mean, rstd});
; #pragma unroll
;                 for (int j = 0; j < 4; ++j) v[j] = v[j] * rstd * g[j] + bb[j];
.LBB0_1276:
	v_mov_b32_e32 v39, v59
	v_mov_b32_e32 v32, v58
	v_mov_b32_e32 v35, v61
	v_mov_b32_e32 v36, v60
	v_pk_add_f32 v[88:89], v[38:39], v[32:33]
	v_mov_b32_e32 v41, v65
	v_add_f32_e32 v45, v88, v89
	v_pk_add_f32 v[88:89], v[34:35], v[36:37]
	v_mov_b32_e32 v40, v64
	v_mov_b32_e32 v43, v63
	v_mov_b32_e32 v42, v62
	v_pk_add_f32 v[88:89], v[88:89], v[88:89] op_sel_hi:[0,1]
	v_mov_b32_e32 v46, v71
	v_mov_b32_e32 v84, v69
	v_mov_b32_e32 v86, v67
	v_add_f32_e32 v45, 0, v45
	v_add_f32_e32 v87, v42, v43
	v_add_f32_e32 v85, v40, v41
	v_mov_b32_e32 v47, v89
	v_pk_add_f32 v[90:91], v[86:87], v[84:85]
	v_pk_add_f32 v[88:89], v[46:47], v[44:45]
	v_lshl_add_u64 v[58:59], v[56:57], 0, s[8:9]
	v_pk_add_f32 v[88:89], v[90:91], v[88:89]
	v_add_co_u32_e32 v66, vcc, s76, v58
	v_add_f32_e32 v45, v88, v89
	v_addc_co_u32_e32 v67, vcc, 0, v59, vcc
	global_load_dwordx2 v[60:61], v[66:67], off offset:2048
	global_load_dwordx2 v[62:63], v[66:67], off offset:2560
	global_load_dwordx2 v[64:65], v[66:67], off offset:3072
	global_load_dwordx2 v[72:73], v[66:67], off offset:3584
	s_nop 1
	v_add_f32_dpp v45, v45, v45 quad_perm:[1,0,3,2] row_mask:0xf bank_mask:0xf
	s_ashr_i32 s11, s10, 31
	s_nop 1
	v_add_f32_dpp v45, v45, v45 quad_perm:[2,3,0,1] row_mask:0xf bank_mask:0xf
	s_nop 1
	v_mov_b32_dpp v47, v45 row_half_mirror row_mask:0xf bank_mask:0xf
	s_nop 1
	v_add_f32_dpp v45, v47, v45 quad_perm:[3,2,1,0] row_mask:0xf bank_mask:0xf
	s_nop 1
	v_mov_b32_dpp v47, v45 row_mirror row_mask:0xf bank_mask:0xf
	s_nop 1
	v_add_f32_dpp v45, v47, v45 row_half_mirror row_mask:0xf bank_mask:0xf
	v_mov_b32_e32 v47, v45
	s_nop 1
	v_permlane16_swap_b32_e32 v47, v45
	v_add_f32_e32 v45, v47, v45
	v_mov_b32_e32 v47, v45
	s_nop 1
	v_permlane32_swap_b32_e32 v47, v45
	v_add_f32_e32 v45, v47, v45
	v_fmac_f32_e32 v38, 0xba800000, v45
	v_fmac_f32_e32 v33, 0xba800000, v45
	v_fmac_f32_e32 v39, 0xba800000, v45
	v_fmac_f32_e32 v32, 0xba800000, v45
	v_mov_b32_e32 v88, v39
	v_mov_b32_e32 v89, v33
	v_mov_b32_e32 v33, v38
	v_pk_mul_f32 v[90:91], v[88:89], v[88:89]
	v_pk_mul_f32 v[38:39], v[32:33], v[32:33]
	v_fmac_f32_e32 v34, 0xba800000, v45
	v_fmac_f32_e32 v37, 0xba800000, v45
	v_fmac_f32_e32 v35, 0xba800000, v45
	v_pk_mov_b32 v[92:93], v[38:39], v[90:91] op_sel:[1,0]
	v_mov_b32_e32 v39, v91
	v_fmac_f32_e32 v36, 0xba800000, v45
	v_mov_b32_e32 v90, v35
	v_mov_b32_e32 v91, v37
	v_mov_b32_e32 v37, v34
	v_pk_add_f32 v[38:39], v[92:93], v[38:39]
	v_pk_mul_f32 v[92:93], v[90:91], v[90:91]
	v_pk_mul_f32 v[34:35], v[36:37], v[36:37]
	v_fmac_f32_e32 v42, 0xba800000, v45
	v_pk_mov_b32 v[94:95], v[34:35], v[92:93] op_sel:[1,0]
	v_mov_b32_e32 v35, v93
	v_pk_add_f32 v[34:35], v[94:95], v[34:35]
	v_fmac_f32_e32 v43, 0xba800000, v45
	v_pk_add_f32 v[34:35], v[34:35], v[34:35] op_sel_hi:[0,1]
	v_fmac_f32_e32 v40, 0xba800000, v45
	v_mul_f32_e32 v34, v42, v42
	v_fmac_f32_e32 v41, 0xba800000, v45
	v_pk_fma_f32 v[92:93], v[42:43], v[42:43], v[34:35] op_sel_hi:[1,1,0]
	v_mul_f32_e32 v34, v40, v40
	v_pk_add_f32 v[38:39], v[38:39], v[38:39] op_sel_hi:[0,1]
	v_pk_fma_f32 v[94:95], v[40:41], v[40:41], v[34:35] op_sel_hi:[1,1,0]
	v_fmac_f32_e32 v44, 0xba800000, v45
	v_fmac_f32_e32 v46, 0xba800000, v45
	v_fmac_f32_e32 v84, 0xba800000, v45
	v_fmac_f32_e32 v86, 0xba800000, v45
	v_mul_f32_e32 v92, v86, v86
	v_mul_f32_e32 v94, v84, v84
	v_mul_f32_e32 v38, v46, v46
	v_mul_f32_e32 v34, v44, v44
	v_pk_add_f32 v[92:93], v[92:93], v[94:95]
	v_pk_add_f32 v[34:35], v[38:39], v[34:35]
	v_mov_b32_e32 v87, v84
	v_pk_add_f32 v[34:35], v[92:93], v[34:35]
	s_waitcnt vmcnt(3)
	v_and_b32_e32 v75, 0xffff0000, v61
	v_add_f32_e32 v34, v34, v35
	s_waitcnt vmcnt(0)
	v_lshlrev_b32_e32 v67, 16, v72
	v_and_b32_e32 v74, 0xffff0000, v60
	v_and_b32_e32 v77, 0xffff0000, v63
	v_and_b32_e32 v76, 0xffff0000, v62
	s_nop 1
	v_add_f32_dpp v34, v34, v34 quad_perm:[1,0,3,2] row_mask:0xf bank_mask:0xf
	v_lshlrev_b32_e32 v71, 16, v73
	v_and_b32_e32 v73, 0xffff0000, v73
	v_lshlrev_b32_e32 v59, 16, v61
	v_lshlrev_b32_e32 v58, 16, v60
	s_nop 1
	v_add_f32_dpp v34, v34, v34 quad_perm:[2,3,0,1] row_mask:0xf bank_mask:0xf
	v_lshlrev_b32_e32 v61, 16, v63
	v_lshlrev_b32_e32 v60, 16, v62
	v_lshlrev_b32_e32 v62, 16, v64
	v_and_b32_e32 v63, 0xffff0000, v64
	s_nop 1
	v_mov_b32_dpp v35, v34 row_half_mirror row_mask:0xf bank_mask:0xf
	s_nop 1
	v_add_f32_dpp v34, v35, v34 quad_perm:[3,2,1,0] row_mask:0xf bank_mask:0xf
	v_lshlrev_b32_e32 v64, 16, v65
	v_and_b32_e32 v65, 0xffff0000, v65
	v_and_b32_e32 v69, 0xffff0000, v72
	s_nop 1
	v_mov_b32_dpp v35, v34 row_mirror row_mask:0xf bank_mask:0xf
	s_nop 1
	v_add_f32_dpp v34, v35, v34 row_half_mirror row_mask:0xf bank_mask:0xf
	v_mov_b32_e32 v35, v34
	s_nop 1
	v_permlane16_swap_b32_e32 v35, v34
	v_add_f32_e32 v34, v35, v34
	v_mov_b32_e32 v35, v34
	s_nop 1
	v_permlane32_swap_b32_e32 v35, v34
	v_add_f32_e32 v34, v35, v34
	v_fmamk_f32 v34, v34, 0x3a800000, v205
	v_cmp_gt_f32_e32 vcc, s34, v34
	v_mul_f32_e32 v35, 0x4f800000, v34
	s_nop 0
	v_cndmask_b32_e32 v34, v34, v35, vcc
	v_sqrt_f32_e32 v35, v34
	s_nop 0
	v_add_u32_e32 v38, -1, v35
	v_fma_f32 v39, -v38, v35, v34
	v_cmp_ge_f32_e64 s[0:1], 0, v39
	v_add_u32_e32 v39, 1, v35
	s_nop 0
	v_cndmask_b32_e64 v38, v35, v38, s[0:1]
	v_fma_f32 v35, -v39, v35, v34
	v_cmp_lt_f32_e64 s[0:1], 0, v35
	s_nop 1
	v_cndmask_b32_e64 v35, v38, v39, s[0:1]
	v_mul_f32_e32 v38, 0x37800000, v35
	v_cndmask_b32_e32 v35, v35, v38, vcc
	v_cmp_class_f32_e32 vcc, v34, v204
	s_nop 1
	v_cndmask_b32_e32 v34, v35, v34, vcc
	v_div_scale_f32 v35, s[0:1], v34, v34, 1.0
	v_rcp_f32_e32 v38, v35
	s_lshl_b64 s[0:1], s[10:11], 12
	s_add_u32 s8, s8, 0x800
	s_addc_u32 s9, s9, 0
	v_fma_f32 v39, -v35, v38, 1.0
	v_fmac_f32_e32 v38, v39, v38
; template <int MODE>
; __device__ __forceinline__ void lnmod_phase(const float* src, float* dst, float* stats, bf16* H, const bf16* zb, const float* lng, const float* lnb, const float* ada_mod  , int lane, int wave, int G) {
;     ...
;                 const float rstd = 1.f / sqrtf(wave_sum(s2) * (1.f / D) + LN_EPS);
;                 if (MODE == 1 && lane == 0) gst<f32x2v>(stats + 2 * (size_t)r, (f32x2v){mean, rstd});
; #pragma unroll
;                 for (int j = 0; j < 4; ++j) v[j] = v[j] * rstd * g[j] + bb[j];
;             }
;             if (MODE == 2) {
; #pragma unroll
;                 for (int j = 0; j < 4; ++j) gst<f32x4>(dst + (size_t)r * D + 4 * lane + 256 * j, v[j]);
	v_div_scale_f32 v39, vcc, 1.0, v34, 1.0
	v_mul_f32_e32 v45, v39, v38
	v_fma_f32 v47, -v35, v45, v39
	v_fmac_f32_e32 v45, v47, v38
	v_fma_f32 v35, -v35, v45, v39
	v_div_fmas_f32 v35, v35, v38, v45
	v_div_fixup_f32 v66, v35, v34, 1.0
	v_mov_b32_e32 v47, v44
	v_pk_mul_f32 v[32:33], v[32:33], v[66:67] op_sel_hi:[1,0]
	v_pk_mul_f32 v[34:35], v[88:89], v[66:67] op_sel_hi:[1,0]
	v_pk_mul_f32 v[36:37], v[36:37], v[66:67] op_sel_hi:[1,0]
	v_pk_mul_f32 v[38:39], v[90:91], v[66:67] op_sel_hi:[1,0]
	v_pk_mul_f32 v[84:85], v[86:87], v[66:67] op_sel_hi:[1,0]
	v_pk_mul_f32 v[44:45], v[46:47], v[66:67] op_sel_hi:[1,0]
	v_pk_fma_f32 v[34:35], v[14:15], v[34:35], v[30:31]
	v_pk_fma_f32 v[32:33], v[12:13], v[32:33], v[28:29]
	v_pk_fma_f32 v[38:39], v[6:7], v[38:39], v[26:27]
	v_pk_fma_f32 v[36:37], v[4:5], v[36:37], v[24:25]
	v_pk_mul_f32 v[88:89], v[42:43], v[66:67] op_sel_hi:[1,0]
	v_pk_mul_f32 v[40:41], v[40:41], v[66:67] op_sel_hi:[1,0]
	v_pk_fma_f32 v[46:47], v[2:3], v[44:45], v[10:11]
	v_pk_fma_f32 v[44:45], v[0:1], v[84:85], v[8:9]
	v_lshl_add_u64 v[84:85], v[50:51], 0, s[0:1]
	s_add_i32 s10, s10, 1
	v_pk_fma_f32 v[42:43], v[18:19], v[40:41], v[22:23]
	v_pk_fma_f32 v[40:41], v[16:17], v[88:89], v[20:21]
	global_store_dwordx4 v[84:85], v[32:35], off
	global_store_dwordx4 v[84:85], v[36:39], off offset:1024
	global_store_dwordx4 v[84:85], v[40:43], off offset:2048
	global_store_dwordx4 v[84:85], v[44:47], off offset:3072
	s_cmpk_eq_u32 s8, 0xf800
	v_mov_b32_e32 v38, v74
	v_mov_b32_e32 v33, v75
	v_mov_b32_e32 v34, v76
	v_mov_b32_e32 v37, v77
	v_mov_b32_e32 v44, v73
	s_cbranch_scc0 .LBB0_1276
; template <int MODE>
; __device__ __forceinline__ void lnmod_phase(const float* src, float* dst, float* stats, bf16* H, const bf16* zb, const float* lng, const float* lnb, const float* ada_mod  , int lane, int wave, int G) {
;     ...
;             if (MODE != 0) {
;                 float s = 0.f;
; #pragma unroll
;                 for (int j = 0; j < 4; ++j) s += (v[j].x + v[j].y) + (v[j].z + v[j].w);
;                 const float mean = wave_sum(s) * (1.f / D); float s2 = 0.f;
; #pragma unroll
;                 for (int j = 0; j < 4; ++j) { v[j] = v[j] - mean; s2 += (v[j].x * v[j].x + v[j].y * v[j].y) + (v[j].z * v[j].z + v[j].w * v[j].w); }
;                 const float rstd = 1.f / sqrtf(wave_sum(s2) * (1.f / D) + LN_EPS);
;                 if (MODE == 1 && lane == 0) gst<f32x2v>(stats + 2 * (size_t)r, (f32x2v){mean, rstd});
; #pragma unroll
;                 for (int j = 0; j < 4; ++j) v[j] = v[j] * rstd * g[j] + bb[j];
;             }
;             if (MODE == 2) {
; #pragma unroll
;                 for (int j = 0; j < 4; ++j) gst<f32x4>(dst + (size_t)r * D + 4 * lane + 256 * j, v[j]);
	v_pk_add_f32 v[32:33], v[58:59], v[74:75]
	v_add_f32_e32 v70, v62, v63
	v_add_f32_e32 v32, v32, v33
	v_add_f32_e32 v66, 0, v32
	v_pk_add_f32 v[32:33], v[60:61], v[76:77]
	v_add_f32_e32 v72, v64, v65
	v_pk_add_f32 v[32:33], v[32:33], v[32:33] op_sel:[0,1] op_sel_hi:[1,0]
	v_pk_add_f32 v[34:35], v[70:71], v[72:73]
	v_mov_b32_e32 v33, v69
	v_pk_add_f32 v[32:33], v[66:67], v[32:33]
	s_lshl_b32 s7, s6, 5
	v_pk_add_f32 v[32:33], v[32:33], v[34:35]
	s_add_i32 s6, s6, s2
	v_add_f32_e32 v32, v32, v33
	s_add_i32 s12, s12, s3
	v_lshl_add_u64 v[56:57], v[56:57], 0, s[4:5]
	s_nop 1
	v_add_f32_dpp v32, v32, v32 quad_perm:[1,0,3,2] row_mask:0xf bank_mask:0xf
	s_nop 1
	v_add_f32_dpp v32, v32, v32 quad_perm:[2,3,0,1] row_mask:0xf bank_mask:0xf
	s_nop 1
	v_mov_b32_dpp v33, v32 row_half_mirror row_mask:0xf bank_mask:0xf
	s_nop 1
	v_add_f32_dpp v32, v33, v32 quad_perm:[3,2,1,0] row_mask:0xf bank_mask:0xf
	s_nop 1
	v_mov_b32_dpp v33, v32 row_mirror row_mask:0xf bank_mask:0xf
	s_nop 1
	v_add_f32_dpp v32, v33, v32 row_half_mirror row_mask:0xf bank_mask:0xf
	v_mov_b32_e32 v33, v32
	s_nop 1
	v_permlane16_swap_b32_e32 v33, v32
	v_add_f32_e32 v32, v33, v32
	v_mov_b32_e32 v33, v32
	s_nop 1
	v_permlane32_swap_b32_e32 v33, v32
	v_add_f32_e32 v46, v33, v32
	v_fmac_f32_e32 v74, 0xba800000, v46
	v_fmac_f32_e32 v75, 0xba800000, v46
	v_fmac_f32_e32 v59, 0xba800000, v46
	v_fmac_f32_e32 v76, 0xba800000, v46
	v_fmac_f32_e32 v77, 0xba800000, v46
	v_fmac_f32_e32 v61, 0xba800000, v46
	v_fmac_f32_e32 v58, 0xba800000, v46
	v_fmac_f32_e32 v60, 0xba800000, v46
	v_mov_b32_e32 v32, v59
	v_mov_b32_e32 v33, v75
	v_mov_b32_e32 v59, v74
	v_mov_b32_e32 v34, v61
	v_mov_b32_e32 v35, v77
	v_mov_b32_e32 v61, v76
	v_pk_mul_f32 v[36:37], v[32:33], v[32:33]
	v_pk_mul_f32 v[38:39], v[58:59], v[58:59]
	v_pk_mul_f32 v[40:41], v[34:35], v[34:35]
	v_pk_mul_f32 v[42:43], v[60:61], v[60:61]
	v_pk_mov_b32 v[44:45], v[38:39], v[36:37] op_sel:[1,0]
	v_mov_b32_e32 v39, v37
	v_pk_mov_b32 v[36:37], v[42:43], v[40:41] op_sel:[1,0]
	v_mov_b32_e32 v43, v41
	v_pk_add_f32 v[36:37], v[36:37], v[42:43]
	v_fmac_f32_e32 v62, 0xba800000, v46
	v_pk_add_f32 v[36:37], v[36:37], v[36:37] op_sel_hi:[0,1]
	v_fmac_f32_e32 v63, 0xba800000, v46
	v_fmac_f32_e32 v64, 0xba800000, v46
	v_mul_f32_e32 v36, v62, v62
	v_pk_add_f32 v[38:39], v[44:45], v[38:39]
	v_fmac_f32_e32 v65, 0xba800000, v46
	v_pk_fma_f32 v[40:41], v[62:63], v[62:63], v[36:37] op_sel_hi:[1,1,0]
	v_mul_f32_e32 v36, v64, v64
	v_pk_add_f32 v[38:39], v[38:39], v[38:39] op_sel_hi:[0,1]
	v_pk_fma_f32 v[42:43], v[64:65], v[64:65], v[36:37] op_sel_hi:[1,1,0]
	v_fmac_f32_e32 v73, 0xba800000, v46
	v_fmac_f32_e32 v71, 0xba800000, v46
	v_fmac_f32_e32 v69, 0xba800000, v46
	v_fmac_f32_e32 v67, 0xba800000, v46
	v_mul_f32_e32 v40, v67, v67
	v_mul_f32_e32 v42, v69, v69
	v_mul_f32_e32 v38, v71, v71
	v_mul_f32_e32 v36, v73, v73
	v_pk_add_f32 v[40:41], v[40:41], v[42:43]
	v_pk_add_f32 v[36:37], v[38:39], v[36:37]
	v_mov_b32_e32 v68, v67
	v_pk_add_f32 v[36:37], v[40:41], v[36:37]
	v_mov_b32_e32 v72, v71
	v_add_f32_e32 v36, v36, v37
	s_nop 1
	v_add_f32_dpp v36, v36, v36 quad_perm:[1,0,3,2] row_mask:0xf bank_mask:0xf
	s_nop 1
	v_add_f32_dpp v36, v36, v36 quad_perm:[2,3,0,1] row_mask:0xf bank_mask:0xf
	s_nop 1
	v_mov_b32_dpp v37, v36 row_half_mirror row_mask:0xf bank_mask:0xf
	s_nop 1
	v_add_f32_dpp v36, v37, v36 quad_perm:[3,2,1,0] row_mask:0xf bank_mask:0xf
	s_nop 1
	v_mov_b32_dpp v37, v36 row_mirror row_mask:0xf bank_mask:0xf
	s_nop 1
	v_add_f32_dpp v36, v37, v36 row_half_mirror row_mask:0xf bank_mask:0xf
	v_mov_b32_e32 v37, v36
	s_nop 1
	v_permlane16_swap_b32_e32 v37, v36
	v_add_f32_e32 v36, v37, v36
	v_mov_b32_e32 v37, v36
	s_nop 1
	v_permlane32_swap_b32_e32 v37, v36
	v_add_f32_e32 v36, v37, v36
	v_fmamk_f32 v36, v36, 0x3a800000, v205
	v_mul_f32_e32 v37, 0x4f800000, v36
	v_cmp_gt_f32_e32 vcc, s34, v36
	s_nop 1
	v_cndmask_b32_e32 v36, v36, v37, vcc
	v_sqrt_f32_e32 v37, v36
	s_nop 0
	v_add_u32_e32 v38, -1, v37
	v_add_u32_e32 v39, 1, v37
	v_fma_f32 v40, -v38, v37, v36
	v_fma_f32 v41, -v39, v37, v36
	v_cmp_ge_f32_e64 s[0:1], 0, v40
	s_nop 1
	v_cndmask_b32_e64 v37, v37, v38, s[0:1]
	v_cmp_lt_f32_e64 s[0:1], 0, v41
	s_nop 1
	v_cndmask_b32_e64 v37, v37, v39, s[0:1]
	v_mul_f32_e32 v38, 0x37800000, v37
	v_cndmask_b32_e32 v37, v37, v38, vcc
	v_cmp_class_f32_e32 vcc, v36, v204
	s_nop 1
	v_cndmask_b32_e32 v36, v37, v36, vcc
	v_div_scale_f32 v37, s[0:1], v36, v36, 1.0
	v_rcp_f32_e32 v38, v37
	v_div_scale_f32 v39, vcc, 1.0, v36, 1.0
	s_or_b32 s0, s7, 31
	v_fma_f32 v40, -v37, v38, 1.0
	v_fmac_f32_e32 v38, v40, v38
	v_mul_f32_e32 v40, v39, v38
	v_fma_f32 v41, -v37, v40, v39
	v_fmac_f32_e32 v40, v41, v38
	v_fma_f32 v37, -v37, v40, v39
	v_div_fmas_f32 v37, v37, v38, v40
	v_div_fixup_f32 v36, v37, v36, 1.0
	v_pk_mul_f32 v[38:39], v[58:59], v[36:37] op_sel_hi:[1,0]
	v_pk_mul_f32 v[32:33], v[32:33], v[36:37] op_sel_hi:[1,0]
	v_pk_fma_f32 v[12:13], v[12:13], v[38:39], v[28:29]
	v_pk_mul_f32 v[28:29], v[60:61], v[36:37] op_sel_hi:[1,0]
	v_pk_fma_f32 v[14:15], v[14:15], v[32:33], v[30:31]
	v_pk_mul_f32 v[30:31], v[34:35], v[36:37] op_sel_hi:[1,0]
	v_pk_fma_f32 v[4:5], v[4:5], v[28:29], v[24:25]
	v_pk_mul_f32 v[24:25], v[62:63], v[36:37] op_sel_hi:[1,0]
	s_ashr_i32 s1, s0, 31
	v_pk_fma_f32 v[6:7], v[6:7], v[30:31], v[26:27]
	v_pk_mul_f32 v[26:27], v[64:65], v[36:37] op_sel_hi:[1,0]
	v_pk_fma_f32 v[16:17], v[16:17], v[24:25], v[20:21]
	v_pk_mul_f32 v[20:21], v[68:69], v[36:37] op_sel_hi:[1,0]
	s_lshl_b64 s[0:1], s[0:1], 12
	v_pk_fma_f32 v[18:19], v[18:19], v[26:27], v[22:23]
	v_pk_mul_f32 v[22:23], v[72:73], v[36:37] op_sel_hi:[1,0]
	v_pk_fma_f32 v[0:1], v[0:1], v[20:21], v[8:9]
	v_lshl_add_u64 v[8:9], v[50:51], 0, s[0:1]
	s_cmpk_gt_i32 s6, 0x7ff
	v_pk_fma_f32 v[2:3], v[2:3], v[22:23], v[10:11]
	global_store_dwordx4 v[8:9], v[12:15], off
	global_store_dwordx4 v[8:9], v[4:7], off offset:1024
	global_store_dwordx4 v[8:9], v[16:19], off offset:2048
	global_store_dwordx4 v[8:9], v[0:3], off offset:3072
	s_cbranch_scc0 .LBB0_1275
